# GEMM: epilogues no longer aligned across the two wave halves; the half-phase stagger persists across units (align barrier kept only for a workgroup's last unit)
# baseline (speedup 1.0000x reference)
; #define PG8_BAR __builtin_amdgcn_s_barrier()
; __device__ __forceinline__ void gemm_generic(LAS unsigned char* lds, const GDesc& d, int G, int bx) {
;     ...
;         if (wr == 0) PG8_BAR;
;         run_epi(d, acc, cur, wr, wc, fr, fq);
.LBB0_267:
	s_and_b64 vcc, s[42:43], s[90:91]
	s_cbranch_vccz .LBB0_269
	s_barrier

; #define PG8_BAR __builtin_amdgcn_s_barrier()
; __device__ __forceinline__ void gemm_generic(LAS unsigned char* lds, const GDesc& d, int G, int bx) {
;     ...
;         if (!has_next) break;
; #pragma unroll
;         for (int a = 0; a < 2; ++a)
; #pragma unroll
;             for (int b = 0; b < 2; ++b)
; #pragma unroll
;                 for (int m = 0; m < 4; ++m)
; #pragma unroll
;                     for (int n = 0; n < 2; ++n) acc[a][b][m][n] = (f32x4){0.f, 0.f, 0.f, 0.f};
;         cur = nxt; cA = nA; cB = nB; ++ui;
;         if (wr == 1) PG8_BAR;
.LBB0_1450:
	s_and_b64 vcc, exec, s[42:43]
	s_mov_b64 s[0:1], -1
	s_cbranch_vccnz .LBB0_244
	v_readlane_b32 s0, v246, 29
	v_readlane_b32 s1, v246, 30
	s_andn2_b64 vcc, exec, s[0:1]
	s_cbranch_vccnz .LBB0_243
	s_branch .LBB0_243
